# plus P1 128x128 tiles: virtual block 1 shares virtual block 0's B (weight) LDS stage, no duplicate B LDS-DMA
# speedup vs baseline: 1.0003x; 1.0003x over previous
; #define LAS __attribute__((address_space(3)))
; #define GLDS_STAGE(st, kt_) do { \
;         _Pragma("unroll") for (int i_ = 0; i_ < FI; ++i_) { \
;             glds16(ap + (size_t)(32 * i_) * lda + (kt_) * 64, l3a + (st) + tid * 16 + i_ * 4096); \
;             glds16(bp + (size_t)(32 * i_) * ldb + (kt_) * 64, l3a + (st) + OPB + tid * 16 + i_ * 4096); } } while (0)
; #define GLDS_STAGE(st, kt_) do { \
;         _Pragma("unroll") for (int i_ = 0; i_ < 4; ++i_) { \
;             glds16(ap + (size_t)(64 * i_) * lda + (kt_) * 64, l3a + (st) + tid * 16 + i_ * 8192); \
;             glds16(bp + (size_t)(64 * i_) * ldb + (kt_) * 64, l3a + (st) + 32768 + tid * 16 + i_ * 8192); } } while (0)
; template <int WT, class Epi>
; DEV void gemm_tile(const bf16_t* __restrict__ A, int lda, const bf16_t* __restrict__ Bt, int ldb, int K, unsigned char* lds, const Epi& epi) {
;     ...
;     f32x4 acc[FI][FI];
; #pragma unroll
;     for (int i = 0; i < FI; ++i)
; #pragma unroll
;         for (int j = 0; j < FI; ++j) acc[i][j] = (f32x4){0.f, 0.f, 0.f, 0.f};
;     const int lrow = tid >> 3, lcs = (tid & 7) ^ (lrow & 7);
;     const bf16_t* ap = A + (size_t)lrow * lda + lcs * 8;
;     const bf16_t* bp = Bt + (size_t)lrow * ldb + lcs * 8;
;     const unsigned l3a = (unsigned)(size_t)(LAS unsigned char*)lds;
;     const int nk = K >> 6;
;     ...
;     constexpr int NSTG = 65536 / STB;
; #pragma unroll
;     for (int s_ = 0; s_ < NSTG - 1; ++s_) if (s_ < nk) GLDS_STAGE(s_ * STB, s_);
;     const int aoff = (wr * WT + fr) * 128, boff = OPB + (wc * WT + fr) * 128, sw = fr & 7;
;     int cur = 0, nxt = (NSTG - 1) * STB;
;     for (int kt = 0; kt < nk; ++kt) {
;         if (NSTG == 4 && kt + 2 < nk) { if (FI == 2) asm volatile("s_waitcnt vmcnt(8)" ::: "memory"); else asm volatile("s_waitcnt vmcnt(0)" ::: "memory"); }
;         else asm volatile("s_waitcnt vmcnt(0)" ::: "memory");
;         __syncthreads();
;         if (kt + NSTG - 1 < nk) GLDS_STAGE(nxt, kt + NSTG - 1);
.LBB0_182:
	s_cmpk_gt_i32 s10, 0xbf
	s_mov_b64 s[4:5], -1
	s_cbranch_scc0 .LBB0_224
	v_mov_b32_e32 v80, v86
	s_add_i32 s6, s10, 0xffffff40
	v_ashrrev_i32_e32 v12, 3, v80
	s_and_b32 s8, s10, 7
	v_xor_b32_e32 v8, v12, v80
	s_lshr_b32 s7, s6, 3
	s_mul_i32 s26, s8, 0x84000
	v_lshlrev_b32_e32 v8, 4, v8
	v_lshl_add_u64 v[2:3], v[134:135], 0, s[26:27]
	v_mad_u64_u32 v[4:5], s[4:5], s7, v87, v[132:133]
	v_and_b32_e32 v74, 0x70, v8
	v_lshlrev_b32_e32 v8, 4, v80
	v_mad_i64_i32 v[6:7], s[4:5], v12, s56, 0
	v_mad_i64_i32 v[2:3], s[4:5], v12, s56, v[2:3]
	v_mad_i64_i32 v[4:5], s[4:5], v12, s56, v[4:5]
	v_add_u32_e32 v83, s53, v8
	v_lshl_add_u64 v[2:3], v[2:3], 0, v[74:75]
	v_add_u32_e32 v8, s55, v8
	v_readfirstlane_b32 s4, v83
	s_mov_b32 s5, m0
	s_mov_b32 m0, s4
	s_nop 0
	global_load_lds_dwordx4 v[2:3], off
	s_mov_b32 m0, s5
	v_lshl_add_u64 v[4:5], v[4:5], 0, v[74:75]
	v_readfirstlane_b32 s5, v8
	s_cmp_lg_u32 s52, 0
	s_cbranch_scc1 .Lshb_0
	s_mov_b32 s9, m0
	s_mov_b32 m0, s5
	s_nop 0
	global_load_lds_dwordx4 v[4:5], off
	s_mov_b32 m0, s9
.Lshb_0:
	v_lshl_add_u64 v[8:9], v[2:3], 0, s[30:31]
	s_add_i32 s9, s4, 0x1000
	s_mov_b32 s11, m0
	s_mov_b32 m0, s9
	s_nop 0
	global_load_lds_dwordx4 v[8:9], off
	s_mov_b32 m0, s11
	v_lshl_add_u64 v[8:9], v[4:5], 0, s[30:31]
	s_add_i32 s9, s5, 0x1000
	s_cmp_lg_u32 s52, 0
	s_cbranch_scc1 .Lshb_1
	s_mov_b32 s11, m0
	s_mov_b32 m0, s9
	s_nop 0
	global_load_lds_dwordx4 v[8:9], off
	s_mov_b32 m0, s11
.Lshb_1:
	v_lshl_add_u64 v[8:9], v[2:3], 0, s[34:35]
	s_add_i32 s9, s4, 0x2000
	s_mov_b32 s11, m0
	s_mov_b32 m0, s9
	s_nop 0
	global_load_lds_dwordx4 v[8:9], off
	s_mov_b32 m0, s11
	v_lshl_add_u64 v[8:9], v[4:5], 0, s[34:35]
	s_add_i32 s9, s5, 0x2000
	s_cmp_lg_u32 s52, 0
	s_cbranch_scc1 .Lshb_2
	s_mov_b32 s11, m0
	s_mov_b32 m0, s9
	s_nop 0
	global_load_lds_dwordx4 v[8:9], off
	s_mov_b32 m0, s11
.Lshb_2:
	v_lshl_add_u64 v[2:3], v[2:3], 0, s[36:37]
	s_addk_i32 s4, 0x3000
	s_mov_b32 s9, m0
	s_mov_b32 m0, s4
	s_nop 0
	global_load_lds_dwordx4 v[2:3], off
	s_mov_b32 m0, s9
	v_lshl_add_u64 v[2:3], v[4:5], 0, s[36:37]
	v_and_b32_e32 v11, 15, v80
	s_add_i32 s4, s5, 0x3000
	s_cmp_lg_u32 s52, 0
	s_cbranch_scc1 .Lshb_3
	s_mov_b32 s5, m0
	s_mov_b32 m0, s4
	s_nop 0
	global_load_lds_dwordx4 v[2:3], off
	s_mov_b32 m0, s5
.Lshb_3:
	v_ashrrev_i32_e32 v2, 1, v80
	v_and_or_b32 v89, v2, s59, v11
	v_lshlrev_b32_e32 v2, 7, v80
	v_lshrrev_b32_e32 v10, 4, v80
	v_bfe_u32 v74, v80, 4, 2
	v_and_b32_e32 v85, 0x2780, v2
	v_subrev_u32_e32 v85, s53, v85
	v_and_b32_e32 v2, 7, v80
	v_bitop3_b32 v3, v10, v2, 3 bitop3:0x6c
	v_bitop3_b32 v2, v74, v2, 4 bitop3:0x36
	v_bitop3_b32 v4, v12, 7, v80 bitop3:0x48
	v_lshlrev_b32_e32 v84, 4, v3
	v_lshlrev_b32_e32 v81, 4, v2
	v_mad_u64_u32 v[2:3], s[4:5], s7, v87, v[6:7]
	v_lshlrev_b32_e32 v4, 4, v4
	v_or_b32_e32 v2, v2, v4
	v_lshl_add_u64 v[76:77], v[66:67], 0, v[2:3]
	v_mad_u64_u32 v[2:3], s[4:5], s8, v87, v[6:7]
	v_or_b32_e32 v2, v2, v4
	v_mov_b32_e32 v42, 0
	v_lshlrev_b32_e32 v82, 7, v89
	v_lshl_add_u64 v[78:79], v[68:69], 0, v[2:3]
	s_mov_b32 s9, 0
	s_mov_b32 s11, 0x8000
	s_mov_b64 s[4:5], 0
	v_mov_b32_e32 v43, v42
	v_mov_b32_e32 v44, v42
	v_mov_b32_e32 v45, v42
	v_mov_b32_e32 v58, v42
	v_mov_b32_e32 v59, v42
	v_mov_b32_e32 v60, v42
	v_mov_b32_e32 v61, v42
	v_mov_b32_e32 v2, v42
	v_mov_b32_e32 v3, v42
	v_mov_b32_e32 v4, v42
	v_mov_b32_e32 v5, v42
	v_mov_b32_e32 v6, v42
	v_mov_b32_e32 v7, v42
	v_mov_b32_e32 v8, v42
	v_mov_b32_e32 v9, v42
	v_mov_b32_e32 v10, v42
	v_mov_b32_e32 v11, v42
	v_mov_b32_e32 v12, v42
	v_mov_b32_e32 v13, v42
	v_mov_b32_e32 v14, v42
	v_mov_b32_e32 v15, v42
	v_mov_b32_e32 v16, v42
	v_mov_b32_e32 v17, v42
	v_mov_b32_e32 v18, v42
	v_mov_b32_e32 v19, v42
	v_mov_b32_e32 v20, v42
	v_mov_b32_e32 v21, v42
	v_mov_b32_e32 v22, v42
	v_mov_b32_e32 v23, v42
	v_mov_b32_e32 v24, v42
	v_mov_b32_e32 v25, v42
	v_mov_b32_e32 v26, v42
	v_mov_b32_e32 v27, v42
	v_mov_b32_e32 v28, v42
	v_mov_b32_e32 v29, v42
	v_mov_b32_e32 v30, v42
	v_mov_b32_e32 v31, v42
	v_mov_b32_e32 v32, v42
	v_mov_b32_e32 v33, v42
	v_mov_b32_e32 v34, v42
	v_mov_b32_e32 v35, v42
	v_mov_b32_e32 v36, v42
	v_mov_b32_e32 v37, v42
	v_mov_b32_e32 v38, v42
	v_mov_b32_e32 v39, v42
	v_mov_b32_e32 v40, v42
	v_mov_b32_e32 v41, v42
	v_mov_b32_e32 v46, v42
	v_mov_b32_e32 v47, v42
	v_mov_b32_e32 v48, v42
	v_mov_b32_e32 v49, v42
	v_mov_b32_e32 v50, v42
	v_mov_b32_e32 v51, v42
	v_mov_b32_e32 v52, v42
	v_mov_b32_e32 v53, v42
	v_mov_b32_e32 v54, v42
	v_mov_b32_e32 v55, v42
	v_mov_b32_e32 v56, v42
	v_mov_b32_e32 v57, v42
	v_mov_b32_e32 v62, v42
	v_mov_b32_e32 v63, v42
	v_mov_b32_e32 v64, v42
	v_mov_b32_e32 v65, v42
.LBB0_184:
	v_add_u32_e32 v94, s11, v83
	s_add_i32 s11, s53, s9
	s_waitcnt vmcnt(0)
	s_barrier
	v_lshl_add_u64 v[90:91], v[78:79], 0, s[4:5]
	v_add_u32_e32 v106, 0x4000, v94
	v_readfirstlane_b32 s12, v94
	v_add_u32_e32 v114, s11, v82
	v_add_u32_e32 v115, s11, v85
	s_mov_b32 s11, m0
	s_mov_b32 m0, s12
	s_nop 0
	global_load_lds_dwordx4 v[90:91], off
	s_mov_b32 m0, s11
	v_lshl_add_u64 v[92:93], v[76:77], 0, s[4:5]
	v_readfirstlane_b32 s11, v106
	s_cmp_lg_u32 s52, 0
	s_cbranch_scc1 .Lshb_4
	s_mov_b32 s38, m0
	s_mov_b32 m0, s11
	s_nop 0
	global_load_lds_dwordx4 v[92:93], off
	s_mov_b32 m0, s38
.Lshb_4:
	v_lshl_add_u64 v[94:95], v[90:91], 0, s[30:31]
	s_add_i32 s13, s12, 0x1000
	s_mov_b32 s40, m0
	s_mov_b32 m0, s13
	s_nop 0
	global_load_lds_dwordx4 v[94:95], off
	s_mov_b32 m0, s40
	v_lshl_add_u64 v[96:97], v[92:93], 0, s[30:31]
	s_add_i32 s38, s11, 0x1000
	s_cmp_lg_u32 s52, 0
	s_cbranch_scc1 .Lshb_5
	s_mov_b32 s13, m0
	s_mov_b32 m0, s38
	s_nop 0
	global_load_lds_dwordx4 v[96:97], off
	s_mov_b32 m0, s13
; #define GLDS_STAGE(st, kt_) do { \
;         _Pragma("unroll") for (int i_ = 0; i_ < FI; ++i_) { \
;             glds16(ap + (size_t)(32 * i_) * lda + (kt_) * 64, l3a + (st) + tid * 16 + i_ * 4096); \
;             glds16(bp + (size_t)(32 * i_) * ldb + (kt_) * 64, l3a + (st) + OPB + tid * 16 + i_ * 4096); } } while (0)
; #define GLDS_STAGE(st, kt_) do { \
;         _Pragma("unroll") for (int i_ = 0; i_ < 4; ++i_) { \
;             glds16(ap + (size_t)(64 * i_) * lda + (kt_) * 64, l3a + (st) + tid * 16 + i_ * 8192); \
;             glds16(bp + (size_t)(64 * i_) * ldb + (kt_) * 64, l3a + (st) + 32768 + tid * 16 + i_ * 8192); } } while (0)
; template <int WT, class Epi>
; DEV void gemm_tile(const bf16_t* __restrict__ A, int lda, const bf16_t* __restrict__ Bt, int ldb, int K, unsigned char* lds, const Epi& epi) {
;     ...
;     for (int kt = 0; kt < nk; ++kt) {
;         if (NSTG == 4 && kt + 2 < nk) { if (FI == 2) asm volatile("s_waitcnt vmcnt(8)" ::: "memory"); else asm volatile("s_waitcnt vmcnt(0)" ::: "memory"); }
;         else asm volatile("s_waitcnt vmcnt(0)" ::: "memory");
;         __syncthreads();
;         if (kt + NSTG - 1 < nk) GLDS_STAGE(nxt, kt + NSTG - 1);
; #pragma unroll
;         for (int kh = 0; kh < 2; ++kh) {
;             bf16x8 af[FI], bfr[FI];
;             const int ch = ((kh * 4 + fq) ^ sw) << 4;
; #pragma unroll
;             for (int i = 0; i < FI; ++i) { af[i] = *(const bf16x8*)(lds + cur + aoff + i * 2048 + ch); bfr[i] = *(const bf16x8*)(lds + cur + boff + i * 2048 + ch); }
; #pragma unroll
;             for (int mi = 0; mi < FI; ++mi)
; #pragma unroll
;                 for (int ni = 0; ni < FI; ++ni) acc[mi][ni] = __builtin_amdgcn_mfma_f32_16x16x32_bf16(bfr[ni], af[mi], acc[mi][ni], 0, 0, 0);
;         }
;         nxt = cur; cur += STB; if (cur == NSTG * STB) cur = 0;
;     }
.Lshb_5:
	v_lshl_add_u64 v[98:99], v[90:91], 0, s[34:35]
	s_add_i32 s26, s12, 0x2000
	s_mov_b32 s13, m0
	s_mov_b32 m0, s26
	s_nop 0
	global_load_lds_dwordx4 v[98:99], off
	s_mov_b32 m0, s13
	v_lshl_add_u64 v[100:101], v[92:93], 0, s[34:35]
	s_add_i32 s39, s11, 0x2000
	s_cmp_lg_u32 s52, 0
	s_cbranch_scc1 .Lshb_6
	s_mov_b32 s13, m0
	s_mov_b32 m0, s39
	s_nop 0
	global_load_lds_dwordx4 v[100:101], off
	s_mov_b32 m0, s13
.Lshb_6:
	v_lshl_add_u64 v[102:103], v[90:91], 0, s[36:37]
	s_addk_i32 s12, 0x3000
	s_mov_b32 s13, m0
	s_mov_b32 m0, s12
	s_nop 0
	global_load_lds_dwordx4 v[102:103], off
	s_mov_b32 m0, s13
	v_lshl_add_u64 v[104:105], v[92:93], 0, s[36:37]
	v_add_u32_e32 v110, v115, v84
	s_addk_i32 s11, 0x3000
	s_cmp_lg_u32 s52, 0
	s_cbranch_scc1 .Lshb_7
	s_mov_b32 s12, m0
	s_mov_b32 m0, s11
	s_nop 0
	global_load_lds_dwordx4 v[104:105], off
	s_mov_b32 m0, s12
.Lshb_7:
	v_add_u32_e32 v116, v114, v84
	ds_read_b128 v[90:93], v110 offset:16384
	ds_read_b128 v[94:97], v110 offset:18432
	ds_read_b128 v[98:101], v116
	ds_read_b128 v[102:105], v116 offset:2048
	ds_read_b128 v[106:109], v110 offset:20480
	ds_read_b128 v[110:113], v110 offset:22528
	s_waitcnt lgkmcnt(3)
	v_mfma_f32_16x16x32_bf16 v[62:65], v[90:93], v[98:101], v[62:65]
	v_add_u32_e32 v114, v114, v81
	v_add_u32_e32 v115, v115, v81
	s_add_i32 s12, s9, 0x8000
	v_mfma_f32_16x16x32_bf16 v[54:57], v[94:97], v[98:101], v[54:57]
	s_cmp_lg_u32 s12, 0x10000
	s_mov_b32 s11, s9
	s_cselect_b32 s9, s12, 0
	s_waitcnt lgkmcnt(1)
	v_mfma_f32_16x16x32_bf16 v[50:53], v[106:109], v[98:101], v[50:53]
	s_add_u32 s4, s4, 0x80
	s_addc_u32 s5, s5, 0
	s_cmpk_eq_i32 s4, 0xf80
	s_waitcnt lgkmcnt(0)
	v_mfma_f32_16x16x32_bf16 v[46:49], v[110:113], v[98:101], v[46:49]
	v_mfma_f32_16x16x32_bf16 v[38:41], v[90:93], v[102:105], v[38:41]
	v_mfma_f32_16x16x32_bf16 v[34:37], v[94:97], v[102:105], v[34:37]
	v_mfma_f32_16x16x32_bf16 v[30:33], v[106:109], v[102:105], v[30:33]
	v_mfma_f32_16x16x32_bf16 v[26:29], v[110:113], v[102:105], v[26:29]
	ds_read_b128 v[98:101], v116 offset:4096
	ds_read_b128 v[102:105], v116 offset:6144
	s_waitcnt lgkmcnt(1)
	v_mfma_f32_16x16x32_bf16 v[22:25], v[90:93], v[98:101], v[22:25]
	v_mfma_f32_16x16x32_bf16 v[18:21], v[94:97], v[98:101], v[18:21]
	v_mfma_f32_16x16x32_bf16 v[14:17], v[106:109], v[98:101], v[14:17]
	v_mfma_f32_16x16x32_bf16 v[10:13], v[110:113], v[98:101], v[10:13]
	s_waitcnt lgkmcnt(0)
	v_mfma_f32_16x16x32_bf16 v[6:9], v[90:93], v[102:105], v[6:9]
	v_mfma_f32_16x16x32_bf16 v[2:5], v[94:97], v[102:105], v[2:5]
	ds_read_b128 v[90:93], v115 offset:16384
	ds_read_b128 v[94:97], v115 offset:18432
	v_mfma_f32_16x16x32_bf16 v[58:61], v[106:109], v[102:105], v[58:61]
	v_mfma_f32_16x16x32_bf16 v[42:45], v[110:113], v[102:105], v[42:45]
	ds_read_b128 v[98:101], v114
	ds_read_b128 v[102:105], v114 offset:2048
	ds_read_b128 v[106:109], v115 offset:20480
	ds_read_b128 v[110:113], v115 offset:22528
	s_waitcnt lgkmcnt(3)
	v_mfma_f32_16x16x32_bf16 v[62:65], v[90:93], v[98:101], v[62:65]
	v_mfma_f32_16x16x32_bf16 v[54:57], v[94:97], v[98:101], v[54:57]
	s_waitcnt lgkmcnt(1)
	v_mfma_f32_16x16x32_bf16 v[50:53], v[106:109], v[98:101], v[50:53]
	s_waitcnt lgkmcnt(0)
	v_mfma_f32_16x16x32_bf16 v[46:49], v[110:113], v[98:101], v[46:49]
	v_mfma_f32_16x16x32_bf16 v[38:41], v[90:93], v[102:105], v[38:41]
	v_mfma_f32_16x16x32_bf16 v[34:37], v[94:97], v[102:105], v[34:37]
	v_mfma_f32_16x16x32_bf16 v[30:33], v[106:109], v[102:105], v[30:33]
	v_mfma_f32_16x16x32_bf16 v[26:29], v[110:113], v[102:105], v[26:29]
	ds_read_b128 v[98:101], v114 offset:4096
	ds_read_b128 v[102:105], v114 offset:6144
	s_waitcnt lgkmcnt(1)
	v_mfma_f32_16x16x32_bf16 v[22:25], v[90:93], v[98:101], v[22:25]
	v_mfma_f32_16x16x32_bf16 v[18:21], v[94:97], v[98:101], v[18:21]
	v_mfma_f32_16x16x32_bf16 v[14:17], v[106:109], v[98:101], v[14:17]
	v_mfma_f32_16x16x32_bf16 v[10:13], v[110:113], v[98:101], v[10:13]
	s_waitcnt lgkmcnt(0)
	v_mfma_f32_16x16x32_bf16 v[6:9], v[90:93], v[102:105], v[6:9]
	v_mfma_f32_16x16x32_bf16 v[2:5], v[94:97], v[102:105], v[2:5]
	v_mfma_f32_16x16x32_bf16 v[58:61], v[106:109], v[102:105], v[58:61]
	v_mfma_f32_16x16x32_bf16 v[42:45], v[110:113], v[102:105], v[42:45]
	s_cbranch_scc0 .LBB0_184
	v_add_u32_e32 v102, s53, v85
	v_add_u32_e32 v103, s53, v82
	v_add_u32_e32 v98, v102, v84
	v_add_u32_e32 v104, v103, v84
	s_waitcnt vmcnt(0)
	s_barrier
; DEV bf16_t f2bf(float f) { return (bf16_t)(cvt_pk_bf16(f, 0.f) & 0xffffu); }
; DEV void store_bf4(bf16_t* p, f32x4 v) { uint2 w; w.x = cvt_pk_bf16(v[0], v[1]); w.y = cvt_pk_bf16(v[2], v[3]); *(uint2*)p = w; }
;     DEV void operator()(int r, int c, f32x4 v) const { store_bf4(dst + (size_t)r * ld + c, v); }
; template <int WT, class Epi>
; DEV void gemm_tile(const bf16_t* __restrict__ A, int lda, const bf16_t* __restrict__ Bt, int ldb, int K, unsigned char* lds, const Epi& epi) {
;     ...
; #pragma unroll
;         for (int kh = 0; kh < 2; ++kh) {
;             bf16x8 af[FI], bfr[FI];
;             const int ch = ((kh * 4 + fq) ^ sw) << 4;
; #pragma unroll
;             for (int i = 0; i < FI; ++i) { af[i] = *(const bf16x8*)(lds + cur + aoff + i * 2048 + ch); bfr[i] = *(const bf16x8*)(lds + cur + boff + i * 2048 + ch); }
; #pragma unroll
;             for (int mi = 0; mi < FI; ++mi)
; #pragma unroll
;                 for (int ni = 0; ni < FI; ++ni) acc[mi][ni] = __builtin_amdgcn_mfma_f32_16x16x32_bf16(bfr[ni], af[mi], acc[mi][ni], 0, 0, 0);
;         }
;         nxt = cur; cur += STB; if (cur == NSTG * STB) cur = 0;
;     }
;     ...
;     __syncthreads();
;     DEV void operator()(int r, int c, f32x4 v) const {
;         const int row = m0 + r, col = n0 + c;
;         if (col < D) {
;             __builtin_nontemporal_store(v, (f32x4*)(out + O_MK + (size_t)row * D + col));
;             store_bf4(mkb + (size_t)row * LDB + col, v);
;         } else {
;             const int cc = col - D, b = row >> 8, m = row & 255;
;             __builtin_nontemporal_store(v, (f32x4*)(out + O_MV + (size_t)row * D + cc));
;             bf16_t* p = mvt + ((size_t)b * D + cc) * LDM + m;
;             p[0] = f2bf(v[0]); p[LDM] = f2bf(v[1]); p[2 * LDM] = f2bf(v[2]); p[3 * LDM] = f2bf(v[3]);
	ds_read_b128 v[76:79], v98 offset:49152
	ds_read_b128 v[90:93], v98 offset:51200
	ds_read_b128 v[82:85], v104 offset:32768
	ds_read_b128 v[94:97], v98 offset:53248
	ds_read_b128 v[98:101], v98 offset:55296
	s_waitcnt lgkmcnt(2)
	v_mfma_f32_16x16x32_bf16 v[62:65], v[76:79], v[82:85], v[62:65]
	v_add_u32_e32 v102, v102, v81
	v_add_u32_e32 v81, v103, v81
	s_lshl_b32 s11, s8, 7
	v_mfma_f32_16x16x32_bf16 v[54:57], v[90:93], v[82:85], v[54:57]
	s_lshl_b32 s4, s7, 7
	s_cmpk_gt_u32 s6, 0x7f
	s_cselect_b64 s[6:7], -1, 0
	s_waitcnt lgkmcnt(1)
	v_mfma_f32_16x16x32_bf16 v[50:53], v[94:97], v[82:85], v[50:53]
	ds_read_b128 v[106:109], v81 offset:34816
	s_and_b64 vcc, exec, s[6:7]
	ds_read_b128 v[110:113], v81 offset:38912
	s_waitcnt lgkmcnt(2)
	v_mfma_f32_16x16x32_bf16 v[46:49], v[98:101], v[82:85], v[46:49]
	ds_read_b128 v[82:85], v104 offset:34816
	s_waitcnt lgkmcnt(0)
	v_mfma_f32_16x16x32_bf16 v[38:41], v[76:79], v[82:85], v[38:41]
	v_mfma_f32_16x16x32_bf16 v[34:37], v[90:93], v[82:85], v[34:37]
	v_mfma_f32_16x16x32_bf16 v[30:33], v[94:97], v[82:85], v[30:33]
	v_mfma_f32_16x16x32_bf16 v[26:29], v[98:101], v[82:85], v[26:29]
	ds_read_b128 v[82:85], v104 offset:36864
	s_waitcnt lgkmcnt(0)
	v_mfma_f32_16x16x32_bf16 v[22:25], v[76:79], v[82:85], v[22:25]
	v_mfma_f32_16x16x32_bf16 v[18:21], v[90:93], v[82:85], v[18:21]
	v_mfma_f32_16x16x32_bf16 v[14:17], v[94:97], v[82:85], v[14:17]
	v_mfma_f32_16x16x32_bf16 v[10:13], v[98:101], v[82:85], v[10:13]
	ds_read_b128 v[82:85], v104 offset:38912
	s_waitcnt lgkmcnt(0)
	v_mfma_f32_16x16x32_bf16 v[6:9], v[76:79], v[82:85], v[6:9]
	ds_read_b128 v[76:79], v102 offset:49152
	v_mfma_f32_16x16x32_bf16 v[2:5], v[90:93], v[82:85], v[2:5]
	v_mfma_f32_16x16x32_bf16 v[90:93], v[94:97], v[82:85], v[58:61]
	v_mfma_f32_16x16x32_bf16 v[94:97], v[98:101], v[82:85], v[42:45]
	ds_read_b128 v[82:85], v102 offset:51200
	ds_read_b128 v[98:101], v102 offset:53248
	ds_read_b128 v[102:105], v102 offset:55296
	ds_read_b128 v[42:45], v81 offset:32768
	s_waitcnt lgkmcnt(0)
	v_mfma_f32_16x16x32_bf16 v[62:65], v[76:79], v[42:45], v[62:65]
	v_mfma_f32_16x16x32_bf16 v[58:61], v[82:85], v[42:45], v[54:57]
	v_mfma_f32_16x16x32_bf16 v[54:57], v[98:101], v[42:45], v[50:53]
	v_mfma_f32_16x16x32_bf16 v[50:53], v[102:105], v[42:45], v[46:49]
	v_mfma_f32_16x16x32_bf16 v[46:49], v[76:79], v[106:109], v[38:41]
	v_mfma_f32_16x16x32_bf16 v[42:45], v[82:85], v[106:109], v[34:37]
	v_mfma_f32_16x16x32_bf16 v[38:41], v[98:101], v[106:109], v[30:33]
	v_mfma_f32_16x16x32_bf16 v[34:37], v[102:105], v[106:109], v[26:29]
	ds_read_b128 v[106:109], v81 offset:36864
	v_and_b32_e32 v81, 64, v80
	v_add_u32_e32 v80, s11, v89
	s_waitcnt lgkmcnt(0)
	v_mfma_f32_16x16x32_bf16 v[30:33], v[76:79], v[106:109], v[22:25]
	s_barrier
	v_mfma_f32_16x16x32_bf16 v[26:29], v[82:85], v[106:109], v[18:21]
	v_mfma_f32_16x16x32_bf16 v[22:25], v[98:101], v[106:109], v[14:17]
	s_nop 2
	v_lshlrev_b32_e32 v14, 2, v74
	v_mfma_f32_16x16x32_bf16 v[18:21], v[102:105], v[106:109], v[10:13]
	v_or3_b32 v74, v14, v81, s4
	s_mov_b64 s[4:5], -1
	v_ashrrev_i32_e32 v81, 31, v80
	v_mfma_f32_16x16x32_bf16 v[10:13], v[82:85], v[110:113], v[2:5]
	v_ashrrev_i32_e32 v84, 8, v80
	v_ashrrev_i32_e32 v85, 31, v84
	s_nop 0
	v_and_b32_e32 v2, 0xcf, v80
	v_mfma_f32_16x16x32_bf16 v[14:17], v[76:79], v[110:113], v[6:9]
	v_lshlrev_b32_e32 v82, 1, v2
	v_add_u32_e32 v78, 0xfffff800, v74
	v_mfma_f32_16x16x32_bf16 v[6:9], v[98:101], v[110:113], v[90:93]
	v_mfma_f32_16x16x32_bf16 v[2:5], v[102:105], v[110:113], v[94:97]
	s_cbranch_vccz .LBB0_187
	v_lshlrev_b64 v[76:77], 13, v[80:81]
	v_lshl_add_u64 v[76:77], s[18:19], 0, v[76:77]
	v_mov_b32_e32 v79, v75
	v_lshl_add_u64 v[76:77], v[78:79], 2, v[76:77]
	global_store_dwordx4 v[76:77], v[62:65], off nt
	v_lshlrev_b64 v[76:77], 11, v[84:85]
	v_lshl_add_u64 v[76:77], v[76:77], 0, v[78:79]
	v_mad_u64_u32 v[90:91], s[4:5], v76, s60, v[162:163]
	v_mad_i32_i24 v91, v77, s60, v91
	v_mov_b32_e32 v83, v75
	v_lshl_add_u64 v[76:77], v[90:91], 0, v[82:83]
	v_cvt_pk_bf16_f32 v79, v62, s0
	global_store_short v[76:77], v79, off
	v_cvt_pk_bf16_f32 v79, v63, s0
	global_store_short v[76:77], v79, off offset:576
	v_cvt_pk_bf16_f32 v79, v64, s0
	global_store_short v[76:77], v79, off offset:1152
	v_cvt_pk_bf16_f32 v79, v65, s0
	global_store_short v[76:77], v79, off offset:1728
	s_mov_b64 s[4:5], 0

; #define LAS __attribute__((address_space(3)))
; #define GLDS_STAGE(st, kt_) do { \
;         _Pragma("unroll") for (int i_ = 0; i_ < FI; ++i_) { \
;             glds16(ap + (size_t)(32 * i_) * lda + (kt_) * 64, l3a + (st) + tid * 16 + i_ * 4096); \
;             glds16(bp + (size_t)(32 * i_) * ldb + (kt_) * 64, l3a + (st) + OPB + tid * 16 + i_ * 4096); } } while (0)
; #define GLDS_STAGE(st, kt_) do { \
;         _Pragma("unroll") for (int i_ = 0; i_ < 4; ++i_) { \
;             glds16(ap + (size_t)(64 * i_) * lda + (kt_) * 64, l3a + (st) + tid * 16 + i_ * 8192); \
;             glds16(bp + (size_t)(64 * i_) * ldb + (kt_) * 64, l3a + (st) + 32768 + tid * 16 + i_ * 8192); } } while (0)
; template <int WT, class Epi>
; DEV void gemm_tile(const bf16_t* __restrict__ A, int lda, const bf16_t* __restrict__ Bt, int ldb, int K, unsigned char* lds, const Epi& epi) {
;     ...
;     f32x4 acc[FI][FI];
; #pragma unroll
;     for (int i = 0; i < FI; ++i)
; #pragma unroll
;         for (int j = 0; j < FI; ++j) acc[i][j] = (f32x4){0.f, 0.f, 0.f, 0.f};
;     const int lrow = tid >> 3, lcs = (tid & 7) ^ (lrow & 7);
;     const bf16_t* ap = A + (size_t)lrow * lda + lcs * 8;
;     const bf16_t* bp = Bt + (size_t)lrow * ldb + lcs * 8;
;     const unsigned l3a = (unsigned)(size_t)(LAS unsigned char*)lds;
;     const int nk = K >> 6;
;     ...
;     constexpr int NSTG = 65536 / STB;
; #pragma unroll
;     for (int s_ = 0; s_ < NSTG - 1; ++s_) if (s_ < nk) GLDS_STAGE(s_ * STB, s_);
;     const int aoff = (wr * WT + fr) * 128, boff = OPB + (wc * WT + fr) * 128, sw = fr & 7;
;     int cur = 0, nxt = (NSTG - 1) * STB;
;     for (int kt = 0; kt < nk; ++kt) {
;         if (NSTG == 4 && kt + 2 < nk) { if (FI == 2) asm volatile("s_waitcnt vmcnt(8)" ::: "memory"); else asm volatile("s_waitcnt vmcnt(0)" ::: "memory"); }
;         else asm volatile("s_waitcnt vmcnt(0)" ::: "memory");
;         __syncthreads();
;         if (kt + NSTG - 1 < nk) GLDS_STAGE(nxt, kt + NSTG - 1);
.LBB0_224:
	s_and_b64 vcc, exec, s[4:5]
	s_cbranch_vccz .LBB0_181
	s_lshl_b32 s4, s10, 7
	v_mov_b32_e32 v80, v86
	s_and_b32 s68, s4, 0x180
	s_bitset1_b32 s68, 13
	v_ashrrev_i32_e32 v12, 3, v80
	v_xor_b32_e32 v8, v12, v80
	s_ashr_i32 s6, s10, 2
	s_mul_i32 s26, s68, 0x1080
	v_lshlrev_b32_e32 v8, 4, v8
	v_lshl_add_u64 v[2:3], v[166:167], 0, s[26:27]
	v_mad_i64_i32 v[4:5], s[4:5], s6, v87, v[130:131]
	v_and_b32_e32 v74, 0x70, v8
	v_lshlrev_b32_e32 v8, 4, v80
	v_mad_i64_i32 v[6:7], s[4:5], v12, s56, 0
	v_mad_i64_i32 v[2:3], s[4:5], v12, s56, v[2:3]
	v_mad_i64_i32 v[4:5], s[4:5], v12, s56, v[4:5]
	v_add_u32_e32 v83, s53, v8
	v_lshl_add_u64 v[2:3], v[2:3], 0, v[74:75]
	v_add_u32_e32 v8, s55, v8
	v_readfirstlane_b32 s4, v83
	s_mov_b32 s5, m0
	s_mov_b32 m0, s4
	s_nop 0
	global_load_lds_dwordx4 v[2:3], off
	s_mov_b32 m0, s5
	v_lshl_add_u64 v[4:5], v[4:5], 0, v[74:75]
	v_readfirstlane_b32 s5, v8
	s_cmp_lg_u32 s52, 0
	s_cbranch_scc1 .Lshb_8
	s_mov_b32 s7, m0
	s_mov_b32 m0, s5
	s_nop 0
	global_load_lds_dwordx4 v[4:5], off
	s_mov_b32 m0, s7
.Lshb_8:
	v_lshl_add_u64 v[8:9], v[2:3], 0, s[30:31]
	s_add_i32 s7, s4, 0x1000
	s_mov_b32 s8, m0
	s_mov_b32 m0, s7
	s_nop 0
	global_load_lds_dwordx4 v[8:9], off
	s_mov_b32 m0, s8
	v_lshl_add_u64 v[8:9], v[4:5], 0, s[30:31]
	s_add_i32 s7, s5, 0x1000
	s_cmp_lg_u32 s52, 0
	s_cbranch_scc1 .Lshb_9
	s_mov_b32 s8, m0
	s_mov_b32 m0, s7
	s_nop 0
	global_load_lds_dwordx4 v[8:9], off
	s_mov_b32 m0, s8
.Lshb_9:
	v_lshl_add_u64 v[8:9], v[2:3], 0, s[34:35]
	s_add_i32 s7, s4, 0x2000
	s_mov_b32 s8, m0
	s_mov_b32 m0, s7
	s_nop 0
	global_load_lds_dwordx4 v[8:9], off
	s_mov_b32 m0, s8
	v_lshl_add_u64 v[8:9], v[4:5], 0, s[34:35]
	s_add_i32 s7, s5, 0x2000
	s_cmp_lg_u32 s52, 0
	s_cbranch_scc1 .Lshb_10
	s_mov_b32 s8, m0
	s_mov_b32 m0, s7
	s_nop 0
	global_load_lds_dwordx4 v[8:9], off
	s_mov_b32 m0, s8
.Lshb_10:
	v_lshl_add_u64 v[2:3], v[2:3], 0, s[36:37]
	s_addk_i32 s4, 0x3000
	s_mov_b32 s7, m0
	s_mov_b32 m0, s4
	s_nop 0
	global_load_lds_dwordx4 v[2:3], off
	s_mov_b32 m0, s7
	v_lshl_add_u64 v[2:3], v[4:5], 0, s[36:37]
	v_and_b32_e32 v11, 15, v80
	s_add_i32 s4, s5, 0x3000
	s_cmp_lg_u32 s52, 0
	s_cbranch_scc1 .Lshb_11
	s_mov_b32 s5, m0
	s_mov_b32 m0, s4
	s_nop 0
	global_load_lds_dwordx4 v[2:3], off
	s_mov_b32 m0, s5
.Lshb_11:
	v_ashrrev_i32_e32 v2, 1, v80
	v_and_or_b32 v81, v2, s59, v11
	v_lshlrev_b32_e32 v2, 7, v80
	v_lshrrev_b32_e32 v10, 4, v80
	v_bfe_u32 v74, v80, 4, 2
	v_and_b32_e32 v89, 0x2780, v2
	v_subrev_u32_e32 v89, s53, v89
	v_and_b32_e32 v2, 7, v80
	v_bitop3_b32 v3, v10, v2, 3 bitop3:0x6c
	v_bitop3_b32 v2, v74, v2, 4 bitop3:0x36
	v_bitop3_b32 v4, v12, 7, v80 bitop3:0x48
	v_lshlrev_b32_e32 v85, 4, v3
	v_lshlrev_b32_e32 v82, 4, v2
	v_mad_i64_i32 v[2:3], s[4:5], s6, v87, v[6:7]
	v_lshlrev_b32_e32 v4, 4, v4
	v_or_b32_e32 v2, v2, v4
	s_and_b32 s4, s10, 3
	v_lshl_add_u64 v[76:77], v[70:71], 0, v[2:3]
	v_mad_u64_u32 v[2:3], s[4:5], s4, v87, v[6:7]
	v_or_b32_e32 v2, v2, v4
	v_mov_b32_e32 v42, 0
	v_lshlrev_b32_e32 v84, 7, v81
	v_lshl_add_u64 v[78:79], v[72:73], 0, v[2:3]
	s_mov_b32 s7, 0
	s_mov_b32 s8, 0x8000
	s_mov_b64 s[4:5], 0
	v_mov_b32_e32 v43, v42
	v_mov_b32_e32 v44, v42
	v_mov_b32_e32 v45, v42
	v_mov_b32_e32 v58, v42
	v_mov_b32_e32 v59, v42
	v_mov_b32_e32 v60, v42
	v_mov_b32_e32 v61, v42
	v_mov_b32_e32 v2, v42
	v_mov_b32_e32 v3, v42
	v_mov_b32_e32 v4, v42
	v_mov_b32_e32 v5, v42
	v_mov_b32_e32 v6, v42
	v_mov_b32_e32 v7, v42
	v_mov_b32_e32 v8, v42
	v_mov_b32_e32 v9, v42
	v_mov_b32_e32 v10, v42
	v_mov_b32_e32 v11, v42
	v_mov_b32_e32 v12, v42
	v_mov_b32_e32 v13, v42
	v_mov_b32_e32 v14, v42
	v_mov_b32_e32 v15, v42
	v_mov_b32_e32 v16, v42
	v_mov_b32_e32 v17, v42
	v_mov_b32_e32 v18, v42
	v_mov_b32_e32 v19, v42
	v_mov_b32_e32 v20, v42
	v_mov_b32_e32 v21, v42
	v_mov_b32_e32 v22, v42
	v_mov_b32_e32 v23, v42
	v_mov_b32_e32 v24, v42
	v_mov_b32_e32 v25, v42
	v_mov_b32_e32 v26, v42
	v_mov_b32_e32 v27, v42
	v_mov_b32_e32 v28, v42
	v_mov_b32_e32 v29, v42
	v_mov_b32_e32 v30, v42
	v_mov_b32_e32 v31, v42
	v_mov_b32_e32 v32, v42
	v_mov_b32_e32 v33, v42
	v_mov_b32_e32 v34, v42
	v_mov_b32_e32 v35, v42
	v_mov_b32_e32 v36, v42
	v_mov_b32_e32 v37, v42
	v_mov_b32_e32 v38, v42
	v_mov_b32_e32 v39, v42
	v_mov_b32_e32 v40, v42
	v_mov_b32_e32 v41, v42
	v_mov_b32_e32 v46, v42
	v_mov_b32_e32 v47, v42
	v_mov_b32_e32 v48, v42
	v_mov_b32_e32 v49, v42
	v_mov_b32_e32 v50, v42
	v_mov_b32_e32 v51, v42
	v_mov_b32_e32 v52, v42
	v_mov_b32_e32 v53, v42
	v_mov_b32_e32 v54, v42
	v_mov_b32_e32 v55, v42
	v_mov_b32_e32 v56, v42
	v_mov_b32_e32 v57, v42
	v_mov_b32_e32 v62, v42
	v_mov_b32_e32 v63, v42
	v_mov_b32_e32 v64, v42
	v_mov_b32_e32 v65, v42
.LBB0_226:
	v_add_u32_e32 v94, s8, v83
	s_add_i32 s8, s53, s7
	s_waitcnt vmcnt(0)
	s_waitcnt vmcnt(63) expcnt(7) lgkmcnt(15)
	s_barrier
	v_lshl_add_u64 v[90:91], v[78:79], 0, s[4:5]
	v_add_u32_e32 v106, 0x4000, v94
	v_readfirstlane_b32 s9, v94
	v_add_u32_e32 v114, s8, v84
	v_add_u32_e32 v115, s8, v89
	s_mov_b32 s8, m0
	s_mov_b32 m0, s9
	s_nop 0
	global_load_lds_dwordx4 v[90:91], off
	s_mov_b32 m0, s8
	v_lshl_add_u64 v[92:93], v[76:77], 0, s[4:5]
	v_readfirstlane_b32 s8, v106
	s_cmp_lg_u32 s52, 0
	s_cbranch_scc1 .Lshb_12
	s_mov_b32 s13, m0
	s_mov_b32 m0, s8
	s_nop 0
	global_load_lds_dwordx4 v[92:93], off
	s_mov_b32 m0, s13
.Lshb_12:
	v_lshl_add_u64 v[94:95], v[90:91], 0, s[30:31]
	s_add_i32 s11, s9, 0x1000
	s_mov_b32 s38, m0
	s_mov_b32 m0, s11
	s_nop 0
	global_load_lds_dwordx4 v[94:95], off
	s_mov_b32 m0, s38
	v_lshl_add_u64 v[96:97], v[92:93], 0, s[30:31]
	s_add_i32 s13, s8, 0x1000
	s_cmp_lg_u32 s52, 0
	s_cbranch_scc1 .Lshb_13
	s_mov_b32 s11, m0
	s_mov_b32 m0, s13
	s_nop 0
	global_load_lds_dwordx4 v[96:97], off
	s_mov_b32 m0, s11
; #define GLDS_STAGE(st, kt_) do { \
;         _Pragma("unroll") for (int i_ = 0; i_ < FI; ++i_) { \
;             glds16(ap + (size_t)(32 * i_) * lda + (kt_) * 64, l3a + (st) + tid * 16 + i_ * 4096); \
;             glds16(bp + (size_t)(32 * i_) * ldb + (kt_) * 64, l3a + (st) + OPB + tid * 16 + i_ * 4096); } } while (0)
; #define GLDS_STAGE(st, kt_) do { \
;         _Pragma("unroll") for (int i_ = 0; i_ < 4; ++i_) { \
;             glds16(ap + (size_t)(64 * i_) * lda + (kt_) * 64, l3a + (st) + tid * 16 + i_ * 8192); \
;             glds16(bp + (size_t)(64 * i_) * ldb + (kt_) * 64, l3a + (st) + 32768 + tid * 16 + i_ * 8192); } } while (0)
; template <int WT, class Epi>
; DEV void gemm_tile(const bf16_t* __restrict__ A, int lda, const bf16_t* __restrict__ Bt, int ldb, int K, unsigned char* lds, const Epi& epi) {
;     ...
;     for (int kt = 0; kt < nk; ++kt) {
;         if (NSTG == 4 && kt + 2 < nk) { if (FI == 2) asm volatile("s_waitcnt vmcnt(8)" ::: "memory"); else asm volatile("s_waitcnt vmcnt(0)" ::: "memory"); }
;         else asm volatile("s_waitcnt vmcnt(0)" ::: "memory");
;         __syncthreads();
;         if (kt + NSTG - 1 < nk) GLDS_STAGE(nxt, kt + NSTG - 1);
; #pragma unroll
;         for (int kh = 0; kh < 2; ++kh) {
;             bf16x8 af[FI], bfr[FI];
;             const int ch = ((kh * 4 + fq) ^ sw) << 4;
; #pragma unroll
;             for (int i = 0; i < FI; ++i) { af[i] = *(const bf16x8*)(lds + cur + aoff + i * 2048 + ch); bfr[i] = *(const bf16x8*)(lds + cur + boff + i * 2048 + ch); }
; #pragma unroll
;             for (int mi = 0; mi < FI; ++mi)
; #pragma unroll
;                 for (int ni = 0; ni < FI; ++ni) acc[mi][ni] = __builtin_amdgcn_mfma_f32_16x16x32_bf16(bfr[ni], af[mi], acc[mi][ni], 0, 0, 0);
;         }
;         nxt = cur; cur += STB; if (cur == NSTG * STB) cur = 0;
;     }
.Lshb_13:
	v_lshl_add_u64 v[98:99], v[90:91], 0, s[34:35]
	s_add_i32 s12, s9, 0x2000
	s_mov_b32 s11, m0
	s_mov_b32 m0, s12
	s_nop 0
	global_load_lds_dwordx4 v[98:99], off
	s_mov_b32 m0, s11
	v_lshl_add_u64 v[100:101], v[92:93], 0, s[34:35]
	s_add_i32 s26, s8, 0x2000
	s_cmp_lg_u32 s52, 0
	s_cbranch_scc1 .Lshb_14
	s_mov_b32 s11, m0
	s_mov_b32 m0, s26
	s_nop 0
	global_load_lds_dwordx4 v[100:101], off
	s_mov_b32 m0, s11
.Lshb_14:
	v_lshl_add_u64 v[102:103], v[90:91], 0, s[36:37]
	s_addk_i32 s9, 0x3000
	s_mov_b32 s11, m0
	s_mov_b32 m0, s9
	s_nop 0
	global_load_lds_dwordx4 v[102:103], off
	s_mov_b32 m0, s11
	v_lshl_add_u64 v[104:105], v[92:93], 0, s[36:37]
	v_add_u32_e32 v110, v115, v85
	s_addk_i32 s8, 0x3000
	s_cmp_lg_u32 s52, 0
	s_cbranch_scc1 .Lshb_15
	s_mov_b32 s9, m0
	s_mov_b32 m0, s8
	s_nop 0
	global_load_lds_dwordx4 v[104:105], off
	s_mov_b32 m0, s9
.Lshb_15:
	v_add_u32_e32 v116, v114, v85
	ds_read_b128 v[90:93], v110 offset:16384
	ds_read_b128 v[94:97], v110 offset:18432
	ds_read_b128 v[98:101], v116
	ds_read_b128 v[102:105], v116 offset:2048
	ds_read_b128 v[106:109], v110 offset:20480
	ds_read_b128 v[110:113], v110 offset:22528
	s_waitcnt lgkmcnt(3)
	v_mfma_f32_16x16x32_bf16 v[62:65], v[90:93], v[98:101], v[62:65]
	v_add_u32_e32 v114, v114, v82
	v_add_u32_e32 v115, v115, v82
	s_add_i32 s9, s7, 0x8000
	v_mfma_f32_16x16x32_bf16 v[54:57], v[94:97], v[98:101], v[54:57]
	s_cmp_lg_u32 s9, 0x10000
	s_mov_b32 s8, s7
	s_cselect_b32 s7, s9, 0
	s_waitcnt lgkmcnt(1)
	v_mfma_f32_16x16x32_bf16 v[50:53], v[106:109], v[98:101], v[50:53]
	s_add_u32 s4, s4, 0x80
	s_addc_u32 s5, s5, 0
	s_cmpk_eq_i32 s4, 0xf80
	s_waitcnt lgkmcnt(0)
	v_mfma_f32_16x16x32_bf16 v[46:49], v[110:113], v[98:101], v[46:49]
	v_mfma_f32_16x16x32_bf16 v[38:41], v[90:93], v[102:105], v[38:41]
	v_mfma_f32_16x16x32_bf16 v[34:37], v[94:97], v[102:105], v[34:37]
	v_mfma_f32_16x16x32_bf16 v[30:33], v[106:109], v[102:105], v[30:33]
	v_mfma_f32_16x16x32_bf16 v[26:29], v[110:113], v[102:105], v[26:29]
	ds_read_b128 v[98:101], v116 offset:4096
	ds_read_b128 v[102:105], v116 offset:6144
	s_waitcnt lgkmcnt(1)
	v_mfma_f32_16x16x32_bf16 v[22:25], v[90:93], v[98:101], v[22:25]
	v_mfma_f32_16x16x32_bf16 v[18:21], v[94:97], v[98:101], v[18:21]
	v_mfma_f32_16x16x32_bf16 v[14:17], v[106:109], v[98:101], v[14:17]
	v_mfma_f32_16x16x32_bf16 v[10:13], v[110:113], v[98:101], v[10:13]
	s_waitcnt lgkmcnt(0)
	v_mfma_f32_16x16x32_bf16 v[6:9], v[90:93], v[102:105], v[6:9]
	v_mfma_f32_16x16x32_bf16 v[2:5], v[94:97], v[102:105], v[2:5]
	ds_read_b128 v[90:93], v115 offset:16384
	ds_read_b128 v[94:97], v115 offset:18432
	v_mfma_f32_16x16x32_bf16 v[58:61], v[106:109], v[102:105], v[58:61]
	v_mfma_f32_16x16x32_bf16 v[42:45], v[110:113], v[102:105], v[42:45]
	ds_read_b128 v[98:101], v114
	ds_read_b128 v[102:105], v114 offset:2048
	ds_read_b128 v[106:109], v115 offset:20480
	ds_read_b128 v[110:113], v115 offset:22528
	s_waitcnt lgkmcnt(3)
	v_mfma_f32_16x16x32_bf16 v[62:65], v[90:93], v[98:101], v[62:65]
	v_mfma_f32_16x16x32_bf16 v[54:57], v[94:97], v[98:101], v[54:57]
	s_waitcnt lgkmcnt(1)
	v_mfma_f32_16x16x32_bf16 v[50:53], v[106:109], v[98:101], v[50:53]
	s_waitcnt lgkmcnt(0)
	v_mfma_f32_16x16x32_bf16 v[46:49], v[110:113], v[98:101], v[46:49]
	v_mfma_f32_16x16x32_bf16 v[38:41], v[90:93], v[102:105], v[38:41]
	v_mfma_f32_16x16x32_bf16 v[34:37], v[94:97], v[102:105], v[34:37]
	v_mfma_f32_16x16x32_bf16 v[30:33], v[106:109], v[102:105], v[30:33]
	v_mfma_f32_16x16x32_bf16 v[26:29], v[110:113], v[102:105], v[26:29]
	ds_read_b128 v[98:101], v114 offset:4096
	ds_read_b128 v[102:105], v114 offset:6144
	s_waitcnt lgkmcnt(1)
	v_mfma_f32_16x16x32_bf16 v[22:25], v[90:93], v[98:101], v[22:25]
	v_mfma_f32_16x16x32_bf16 v[18:21], v[94:97], v[98:101], v[18:21]
	v_mfma_f32_16x16x32_bf16 v[14:17], v[106:109], v[98:101], v[14:17]
	v_mfma_f32_16x16x32_bf16 v[10:13], v[110:113], v[98:101], v[10:13]
	s_waitcnt lgkmcnt(0)
	v_mfma_f32_16x16x32_bf16 v[6:9], v[90:93], v[102:105], v[6:9]
	v_mfma_f32_16x16x32_bf16 v[2:5], v[94:97], v[102:105], v[2:5]
	v_mfma_f32_16x16x32_bf16 v[58:61], v[106:109], v[102:105], v[58:61]
	v_mfma_f32_16x16x32_bf16 v[42:45], v[110:113], v[102:105], v[42:45]
	s_cbranch_scc0 .LBB0_226
	v_add_u32_e32 v83, s53, v89
	v_add_u32_e32 v89, v83, v85
	s_waitcnt vmcnt(0)
	s_barrier
; DEV void store_bf4(bf16_t* p, f32x4 v) { uint2 w; w.x = cvt_pk_bf16(v[0], v[1]); w.y = cvt_pk_bf16(v[2], v[3]); *(uint2*)p = w; }
;     DEV void operator()(int r, int c, f32x4 v) const { store_bf4(dst + (size_t)r * ld + c, v); }
; template <int WT, class Epi>
; DEV void gemm_tile(const bf16_t* __restrict__ A, int lda, const bf16_t* __restrict__ Bt, int ldb, int K, unsigned char* lds, const Epi& epi) {
;     ...
; #pragma unroll
;         for (int kh = 0; kh < 2; ++kh) {
;             bf16x8 af[FI], bfr[FI];
;             const int ch = ((kh * 4 + fq) ^ sw) << 4;
; #pragma unroll
;             for (int i = 0; i < FI; ++i) { af[i] = *(const bf16x8*)(lds + cur + aoff + i * 2048 + ch); bfr[i] = *(const bf16x8*)(lds + cur + boff + i * 2048 + ch); }
; #pragma unroll
;             for (int mi = 0; mi < FI; ++mi)
; #pragma unroll
;                 for (int ni = 0; ni < FI; ++ni) acc[mi][ni] = __builtin_amdgcn_mfma_f32_16x16x32_bf16(bfr[ni], af[mi], acc[mi][ni], 0, 0, 0);
;         }
;         nxt = cur; cur += STB; if (cur == NSTG * STB) cur = 0;
;     }
;     ...
;     __syncthreads();
;     DEV void operator()(int r, int c, f32x4 v) const {
;         const int row = m0 + r, col = n0 + c;
;         if (col < NPJ) {
;             store_bf4(proj + (size_t)row * NPJ + col, v);
;             const bool isconv = col < 3072, ispool = (col >= C_U && col < C_ZB);
;             if (isconv || ispool) {
;                 if (row < TP) {
;                     const int b = row >> 11, t = row & 2047;
;                     if (isconv) { if (t >= 2045) *(f32x4*)(out + O_CP + ((size_t)(b * 3 + (t - 2045))) * 3072 + col) = v; }
;                     else { if (t >= 2033) *(f32x4*)(out + O_PP + ((size_t)(b * 15 + (t - 2033))) * 1024 + (col - C_U)) = v; }
	ds_read_b128 v[76:79], v89 offset:49152
	ds_read_b128 v[94:97], v89 offset:51200
	ds_read_b128 v[98:101], v89 offset:53248
	ds_read_b128 v[102:105], v89 offset:55296
	v_add_u32_e32 v84, s53, v84
	v_add_u32_e32 v85, v84, v85
	ds_read_b128 v[90:93], v85 offset:32768
	v_add_u32_e32 v89, v84, v82
	ds_read_b128 v[110:113], v89 offset:36864
	s_waitcnt lgkmcnt(1)
	v_mfma_f32_16x16x32_bf16 v[62:65], v[76:79], v[90:93], v[62:65]
	ds_read_b128 v[114:117], v89 offset:38912
	s_lshl_b32 s4, s6, 7
	s_and_b32 s26, s10, 0x7ffffe0
	v_mfma_f32_16x16x32_bf16 v[54:57], v[94:97], v[90:93], v[54:57]
	s_cmpk_lg_i32 s26, 0x80
	s_cselect_b64 s[44:45], -1, 0
	v_mfma_f32_16x16x32_bf16 v[50:53], v[98:101], v[90:93], v[50:53]
	v_mfma_f32_16x16x32_bf16 v[46:49], v[102:105], v[90:93], v[46:49]
	ds_read_b128 v[90:93], v85 offset:34816
	s_waitcnt lgkmcnt(0)
	v_mfma_f32_16x16x32_bf16 v[38:41], v[76:79], v[90:93], v[38:41]
	v_mfma_f32_16x16x32_bf16 v[34:37], v[94:97], v[90:93], v[34:37]
	v_mfma_f32_16x16x32_bf16 v[30:33], v[98:101], v[90:93], v[30:33]
	v_mfma_f32_16x16x32_bf16 v[26:29], v[102:105], v[90:93], v[26:29]
	ds_read_b128 v[90:93], v85 offset:36864
	s_waitcnt lgkmcnt(0)
	v_mfma_f32_16x16x32_bf16 v[22:25], v[76:79], v[90:93], v[22:25]
	v_mfma_f32_16x16x32_bf16 v[18:21], v[94:97], v[90:93], v[18:21]
	v_mfma_f32_16x16x32_bf16 v[14:17], v[98:101], v[90:93], v[14:17]
	v_mfma_f32_16x16x32_bf16 v[10:13], v[102:105], v[90:93], v[10:13]
	ds_read_b128 v[90:93], v85 offset:38912
	s_waitcnt lgkmcnt(0)
	v_mfma_f32_16x16x32_bf16 v[6:9], v[76:79], v[90:93], v[6:9]
	v_add_u32_e32 v76, v83, v82
	ds_read_b128 v[82:85], v76 offset:51200
	ds_read_b128 v[106:109], v76 offset:55296
	v_mfma_f32_16x16x32_bf16 v[2:5], v[94:97], v[90:93], v[2:5]
	v_mfma_f32_16x16x32_bf16 v[94:97], v[98:101], v[90:93], v[58:61]
	ds_read_b128 v[98:101], v76 offset:49152
	v_mfma_f32_16x16x32_bf16 v[90:93], v[102:105], v[90:93], v[42:45]
	ds_read_b128 v[102:105], v76 offset:53248
	ds_read_b128 v[76:79], v89 offset:34816
	s_nop 0
	ds_read_b128 v[42:45], v89 offset:32768
	s_waitcnt lgkmcnt(0)
	v_mfma_f32_16x16x32_bf16 v[62:65], v[98:101], v[42:45], v[62:65]
	s_barrier
	v_mfma_f32_16x16x32_bf16 v[58:61], v[82:85], v[42:45], v[54:57]
	v_mfma_f32_16x16x32_bf16 v[54:57], v[102:105], v[42:45], v[50:53]
	v_mfma_f32_16x16x32_bf16 v[50:53], v[106:109], v[42:45], v[46:49]
	v_mfma_f32_16x16x32_bf16 v[46:49], v[98:101], v[76:79], v[38:41]
	v_mfma_f32_16x16x32_bf16 v[42:45], v[82:85], v[76:79], v[34:37]
	v_mfma_f32_16x16x32_bf16 v[38:41], v[102:105], v[76:79], v[30:33]
	v_mfma_f32_16x16x32_bf16 v[34:37], v[106:109], v[76:79], v[26:29]
	v_and_b32_e32 v76, 64, v80
	v_mfma_f32_16x16x32_bf16 v[26:29], v[82:85], v[110:113], v[18:21]
	s_nop 2
	v_lshlrev_b32_e32 v18, 2, v74
	v_add_u32_e32 v74, s68, v81
	v_or3_b32 v76, v18, v76, s4
	v_mfma_f32_16x16x32_bf16 v[30:33], v[98:101], v[110:113], v[22:25]
	v_ashrrev_i32_e32 v77, 31, v76
	v_cmp_lt_i32_e32 vcc, s62, v76
	s_and_b64 s[38:39], s[44:45], vcc
	v_mfma_f32_16x16x32_bf16 v[22:25], v[102:105], v[110:113], v[14:17]
	v_cmp_gt_i32_e64 s[12:13], s57, v74
	s_nor_b64 s[8:9], s[12:13], s[38:39]
	s_nop 0
	v_mad_i64_i32 v[14:15], s[4:5], v74, s58, v[172:173]
	v_lshl_add_u64 v[78:79], v[76:77], 1, v[14:15]
	v_mfma_f32_16x16x32_bf16 v[18:21], v[106:109], v[110:113], v[10:13]
	v_cmp_gt_i32_e64 s[4:5], s61, v76
	s_nop 1
	v_cvt_pk_bf16_f32 v10, v62, v63
	v_cvt_pk_bf16_f32 v11, v64, v65
	global_store_dwordx2 v[78:79], v[10:11], off
	v_mfma_f32_16x16x32_bf16 v[10:13], v[82:85], v[114:117], v[2:5]
	s_nop 2
	v_add_u32_e32 v2, 0xffffe000, v74
	v_mfma_f32_16x16x32_bf16 v[14:17], v[98:101], v[114:117], v[6:9]
	v_lshrrev_b32_e32 v82, 2, v2
	v_mfma_f32_16x16x32_bf16 v[6:9], v[102:105], v[114:117], v[94:97]
	v_mfma_f32_16x16x32_bf16 v[2:5], v[106:109], v[114:117], v[90:93]
	s_and_saveexec_b64 s[6:7], s[8:9]
	s_cbranch_execz .LBB0_234
	v_and_b32_e32 v74, 3, v80
	s_and_saveexec_b64 s[8:9], s[4:5]
	s_xor_b64 s[8:9], exec, s[8:9]
	s_cbranch_execz .LBB0_232
	v_cmp_ne_u32_e32 vcc, 0, v74
	s_and_saveexec_b64 s[10:11], vcc
	s_cbranch_execz .LBB0_231
	v_lshl_add_u32 v83, v82, 1, v82
	v_add3_u32 v74, v74, v83, -1
	v_mov_b64_e32 v[84:85], s[22:23]
	v_mad_u64_u32 v[84:85], s[40:41], v74, s58, v[84:85]
	v_lshl_add_u64 v[84:85], v[76:77], 2, v[84:85]
	global_store_dwordx4 v[84:85], v[62:65], off
